# hot loop heads (four GEMM K-loops, attention main and band loops) aligned to 64 bytes with s_nop fill
# speedup vs baseline: 1.0045x; 1.0036x over previous
.LBB0_319:
	s_ashr_i32 s63, s62, 31
	s_lshl_b64 s[64:65], s[62:63], 20
	s_add_u32 s64, s18, s64
	s_addc_u32 s65, s19, s65
	s_and_b64 s[66:67], s[0:1], exec
	s_cselect_b32 s63, s65, s69
	s_cselect_b32 s96, s64, s68
	s_ashr_i32 s59, s58, 31
	s_lshl_b64 s[66:67], s[58:59], 20
	s_add_u32 s66, s56, s66
	s_addc_u32 s67, s57, s67
	s_and_b64 s[72:73], s[0:1], exec
	s_cselect_b32 s59, s67, s71
	s_cselect_b32 s97, s66, s70
	s_add_u32 s68, s68, 0x80080
	s_addc_u32 s69, s69, 0
	s_add_u32 vcc_lo, s70, 0x100
	v_mov_b32_e32 v0, 0
	s_addc_u32 vcc_hi, s71, 0
	s_mov_b32 s87, -2
	v_mov_b32_e32 v1, v0
	v_mov_b32_e32 v2, v0
	v_mov_b32_e32 v3, v0
	v_mov_b32_e32 v8, v0
	v_mov_b32_e32 v9, v0
	v_mov_b32_e32 v10, v0
	v_mov_b32_e32 v11, v0
	v_mov_b32_e32 v16, v0
	v_mov_b32_e32 v17, v0
	v_mov_b32_e32 v18, v0
	v_mov_b32_e32 v19, v0
	v_mov_b32_e32 v24, v0
	v_mov_b32_e32 v25, v0
	v_mov_b32_e32 v26, v0
	v_mov_b32_e32 v27, v0
	v_mov_b32_e32 v32, v0
	v_mov_b32_e32 v33, v0
	v_mov_b32_e32 v34, v0
	v_mov_b32_e32 v35, v0
	v_mov_b32_e32 v40, v0
	v_mov_b32_e32 v41, v0
	v_mov_b32_e32 v42, v0
	v_mov_b32_e32 v43, v0
	v_mov_b32_e32 v48, v0
	v_mov_b32_e32 v49, v0
	v_mov_b32_e32 v50, v0
	v_mov_b32_e32 v51, v0
	v_mov_b32_e32 v56, v0
	v_mov_b32_e32 v57, v0
	v_mov_b32_e32 v58, v0
	v_mov_b32_e32 v59, v0
	v_mov_b32_e32 v4, v0
	v_mov_b32_e32 v5, v0
	v_mov_b32_e32 v6, v0
	v_mov_b32_e32 v7, v0
	v_mov_b32_e32 v12, v0
	v_mov_b32_e32 v13, v0
	v_mov_b32_e32 v14, v0
	v_mov_b32_e32 v15, v0
	v_mov_b32_e32 v20, v0
	v_mov_b32_e32 v21, v0
	v_mov_b32_e32 v22, v0
	v_mov_b32_e32 v23, v0
	v_mov_b32_e32 v28, v0
	v_mov_b32_e32 v29, v0
	v_mov_b32_e32 v30, v0
	v_mov_b32_e32 v31, v0
	v_mov_b32_e32 v36, v0
	v_mov_b32_e32 v37, v0
	v_mov_b32_e32 v38, v0
	v_mov_b32_e32 v39, v0
	v_mov_b32_e32 v44, v0
	v_mov_b32_e32 v45, v0
	v_mov_b32_e32 v46, v0
	v_mov_b32_e32 v47, v0
	v_mov_b32_e32 v52, v0
	v_mov_b32_e32 v53, v0
	v_mov_b32_e32 v54, v0
	v_mov_b32_e32 v55, v0
	v_mov_b32_e32 v60, v0
	v_mov_b32_e32 v61, v0
	v_mov_b32_e32 v62, v0
	v_mov_b32_e32 v63, v0
	v_mov_b32_e32 v64, v0
	v_mov_b32_e32 v65, v0
	v_mov_b32_e32 v66, v0
	v_mov_b32_e32 v67, v0
	v_mov_b32_e32 v72, v0
	v_mov_b32_e32 v73, v0
	v_mov_b32_e32 v74, v0
	v_mov_b32_e32 v75, v0
	v_mov_b32_e32 v80, v0
	v_mov_b32_e32 v81, v0
	v_mov_b32_e32 v82, v0
	v_mov_b32_e32 v83, v0
	v_mov_b32_e32 v88, v0
	v_mov_b32_e32 v89, v0
	v_mov_b32_e32 v90, v0
	v_mov_b32_e32 v91, v0
	v_mov_b32_e32 v96, v0
	v_mov_b32_e32 v97, v0
	v_mov_b32_e32 v98, v0
	v_mov_b32_e32 v99, v0
	v_mov_b32_e32 v104, v0
	v_mov_b32_e32 v105, v0
	v_mov_b32_e32 v106, v0
	v_mov_b32_e32 v107, v0
	v_mov_b32_e32 v112, v0
	v_mov_b32_e32 v113, v0
	v_mov_b32_e32 v114, v0
	v_mov_b32_e32 v115, v0
	v_mov_b32_e32 v120, v0
	v_mov_b32_e32 v121, v0
	v_mov_b32_e32 v122, v0
	v_mov_b32_e32 v123, v0
	v_mov_b32_e32 v68, v0
	v_mov_b32_e32 v69, v0
	v_mov_b32_e32 v70, v0
	v_mov_b32_e32 v71, v0
	v_mov_b32_e32 v76, v0
	v_mov_b32_e32 v77, v0
	v_mov_b32_e32 v78, v0
	v_mov_b32_e32 v79, v0
	v_mov_b32_e32 v84, v0
	v_mov_b32_e32 v85, v0
	v_mov_b32_e32 v86, v0
	v_mov_b32_e32 v87, v0
	v_mov_b32_e32 v92, v0
	v_mov_b32_e32 v93, v0
	v_mov_b32_e32 v94, v0
	v_mov_b32_e32 v95, v0
	v_mov_b32_e32 v100, v0
	v_mov_b32_e32 v101, v0
	v_mov_b32_e32 v102, v0
	v_mov_b32_e32 v103, v0
	v_mov_b32_e32 v108, v0
	v_mov_b32_e32 v109, v0
	v_mov_b32_e32 v110, v0
	v_mov_b32_e32 v111, v0
	v_mov_b32_e32 v116, v0
	v_mov_b32_e32 v117, v0
	v_mov_b32_e32 v118, v0
	v_mov_b32_e32 v119, v0
	v_mov_b32_e32 v124, v0
	v_mov_b32_e32 v125, v0
	v_mov_b32_e32 v126, v0
	v_mov_b32_e32 v127, v0
	.p2alignl 6, 3212836864

.LBB0_427:
	v_exp_f32_e32 v0, v2
	v_exp_f32_e32 v3, v3
	v_exp_f32_e32 v4, v4
	v_exp_f32_e32 v5, v5
	v_exp_f32_e32 v6, v6
	v_exp_f32_e32 v2, v18
	v_exp_f32_e32 v18, v19
	v_exp_f32_e32 v19, v20
	v_exp_f32_e32 v20, v21
	v_exp_f32_e32 v21, v22
	v_exp_f32_e32 v7, v7
	v_exp_f32_e32 v22, v23
	v_exp_f32_e32 v23, v24
	v_exp_f32_e32 v24, v25
	v_exp_f32_e32 v25, v26
	v_exp_f32_e32 v26, v27
	v_exp_f32_e32 v27, v28
	v_exp_f32_e32 v28, v29
	v_exp_f32_e32 v29, v30
	v_exp_f32_e32 v30, v31
	v_exp_f32_e32 v31, v32
	v_exp_f32_e32 v32, v33
	v_add_f32_e32 v33, v0, v3
	v_exp_f32_e32 v8, v8
	v_add_f32_e32 v33, v4, v33
	v_exp_f32_e32 v9, v9
	v_add_f32_e32 v33, v5, v33
	v_exp_f32_e32 v10, v10
	v_add_f32_e32 v33, v6, v33
	v_exp_f32_e32 v11, v11
	v_add_f32_e32 v33, v7, v33
	v_exp_f32_e32 v12, v12
	v_add_f32_e32 v33, v8, v33
	v_exp_f32_e32 v13, v13
	v_add_f32_e32 v33, v9, v33
	v_exp_f32_e32 v14, v14
	v_add_f32_e32 v33, v10, v33
	v_exp_f32_e32 v15, v15
	v_add_f32_e32 v33, v11, v33
	v_exp_f32_e32 v16, v16
	v_add_f32_e32 v33, v12, v33
	v_exp_f32_e32 v17, v17
	v_add_f32_e32 v33, v13, v33
	v_add_f32_e32 v33, v14, v33
	v_add_f32_e32 v33, v15, v33
	v_add_f32_e32 v33, v16, v33
	v_add_f32_e32 v33, v17, v33
	v_add_f32_e32 v33, v2, v33
	v_add_f32_e32 v33, v18, v33
	v_add_f32_e32 v33, v19, v33
	v_add_f32_e32 v33, v20, v33
	v_add_f32_e32 v33, v21, v33
	v_add_f32_e32 v33, v22, v33
	v_add_f32_e32 v33, v23, v33
	v_add_f32_e32 v33, v24, v33
	v_add_f32_e32 v33, v25, v33
	v_add_f32_e32 v33, v26, v33
	v_add_f32_e32 v33, v27, v33
	v_add_f32_e32 v33, v28, v33
	v_add_f32_e32 v33, v29, v33
	v_add_f32_e32 v33, v30, v33
	v_add_f32_e32 v33, v31, v33
	v_add_f32_e32 v33, v32, v33
	v_cvt_pk_bf16_f32 v152, v0, v3
	v_cvt_pk_bf16_f32 v153, v4, v5
	v_cvt_pk_bf16_f32 v154, v6, v7
	v_cvt_pk_bf16_f32 v155, v8, v9
	v_cvt_pk_bf16_f32 v148, v10, v11
	v_cvt_pk_bf16_f32 v149, v12, v13
	v_cvt_pk_bf16_f32 v150, v14, v15
	v_cvt_pk_bf16_f32 v151, v16, v17
	v_cvt_pk_bf16_f32 v144, v2, v18
	v_cvt_pk_bf16_f32 v145, v19, v20
	v_cvt_pk_bf16_f32 v146, v21, v22
	v_cvt_pk_bf16_f32 v147, v23, v24
	v_cvt_pk_bf16_f32 v140, v25, v26
	v_cvt_pk_bf16_f32 v141, v27, v28
	v_cvt_pk_bf16_f32 v142, v29, v30
	v_cvt_pk_bf16_f32 v143, v31, v32
	s_cmp_lt_i32 s50, 7
	v_add_f32_e32 v229, 0, v33
	s_cbranch_scc1 .LBB0_472
	s_and_b32 s42, s65, 7
	s_lshl_b32 s42, s42, 8
	s_add_i32 s43, s50, -5
	s_or_b32 s42, s4, s42
	s_add_u32 s44, s54, s42
	v_mov_b32_e32 v16, 0
	s_addc_u32 s45, s55, s5
	s_mov_b32 s42, 1
	s_movk_i32 s74, 0x4000
	s_movk_i32 s51, 0x2000
	s_mov_b32 s48, 0
	s_mov_b32 s77, 0
	s_movk_i32 s76, 0x2000
	s_movk_i32 s75, 0x4000
	v_mov_b32_e32 v17, v16
	v_mov_b32_e32 v18, v16
	v_mov_b32_e32 v19, v16
	v_mov_b32_e32 v20, v16
	v_mov_b32_e32 v21, v16
	v_mov_b32_e32 v22, v16
	v_mov_b32_e32 v23, v16
	v_mov_b32_e32 v24, v16
	v_mov_b32_e32 v25, v16
	v_mov_b32_e32 v26, v16
	v_mov_b32_e32 v27, v16
	v_mov_b32_e32 v28, v16
	v_mov_b32_e32 v29, v16
	v_mov_b32_e32 v30, v16
	v_mov_b32_e32 v31, v16
	v_mov_b32_e32 v32, v16
	v_mov_b32_e32 v33, v16
	v_mov_b32_e32 v34, v16
	v_mov_b32_e32 v35, v16
	v_mov_b32_e32 v36, v16
	v_mov_b32_e32 v37, v16
	v_mov_b32_e32 v38, v16
	v_mov_b32_e32 v39, v16
	v_mov_b32_e32 v40, v16
	v_mov_b32_e32 v41, v16
	v_mov_b32_e32 v42, v16
	v_mov_b32_e32 v43, v16
	v_mov_b32_e32 v44, v16
	v_mov_b32_e32 v45, v16
	v_mov_b32_e32 v46, v16
	v_mov_b32_e32 v47, v16
	v_mov_b32_e32 v48, v16
	v_mov_b32_e32 v49, v16
	v_mov_b32_e32 v50, v16
	v_mov_b32_e32 v51, v16
	v_mov_b32_e32 v52, v16
	v_mov_b32_e32 v53, v16
	v_mov_b32_e32 v54, v16
	v_mov_b32_e32 v55, v16
	v_mov_b32_e32 v56, v16
	v_mov_b32_e32 v57, v16
	v_mov_b32_e32 v58, v16
	v_mov_b32_e32 v59, v16
	v_mov_b32_e32 v60, v16
	v_mov_b32_e32 v61, v16
	v_mov_b32_e32 v62, v16
	v_mov_b32_e32 v63, v16
	v_mov_b32_e32 v64, v16
	v_mov_b32_e32 v65, v16
	v_mov_b32_e32 v66, v16
	v_mov_b32_e32 v67, v16
	v_mov_b32_e32 v68, v16
	v_mov_b32_e32 v69, v16
	v_mov_b32_e32 v70, v16
	v_mov_b32_e32 v71, v16
	v_mov_b32_e32 v72, v16
	v_mov_b32_e32 v73, v16
	v_mov_b32_e32 v74, v16
	v_mov_b32_e32 v75, v16
	v_mov_b32_e32 v76, v16
	v_mov_b32_e32 v77, v16
	v_mov_b32_e32 v78, v16
	v_mov_b32_e32 v79, v16
	.p2alignl 6, 3212836864

.LBB0_432:
	s_andn2_b64 vcc, exec, s[44:45]
	s_cbranch_vccnz .LBB0_470
	s_mov_b32 s43, s39
	s_add_i32 s77, s50, -2
	s_lshr_b32 s78, s71, 1
	s_sub_i32 s79, 0, s50
	s_add_i32 s80, s42, 4
	s_lshl_b64 s[42:43], s[42:43], 17
	s_add_u32 s4, s4, s42
	s_addc_u32 s5, s5, s43
	s_and_b32 s42, s65, 7
	s_lshl_b32 s42, s42, 8
	s_or_b32 s4, s4, s42
	s_add_u32 s42, s56, s4
	s_addc_u32 s43, s57, s5
	.p2alignl 6, 3212836864

.LBB0_544:
	s_ashr_i32 s45, s44, 31
	s_lshl_b64 s[46:47], s[44:45], 20
	s_add_u32 s46, s20, s46
	s_addc_u32 s47, s21, s47
	s_and_b64 s[48:49], s[4:5], exec
	s_cselect_b32 s45, s47, s55
	s_cselect_b32 s51, s46, s54
	s_ashr_i32 s43, s42, 31
	s_lshl_b64 s[48:49], s[42:43], 20
	s_add_u32 s48, s6, s48
	s_addc_u32 s49, s7, s49
	s_and_b64 s[58:59], s[4:5], exec
	s_cselect_b32 s43, s49, s57
	s_cselect_b32 s73, s48, s56
	s_add_u32 s54, s54, 0x80080
	s_addc_u32 s55, s55, 0
	s_add_u32 s74, s56, 0x100
	v_mov_b32_e32 v0, 0
	s_addc_u32 s75, s57, 0
	s_mov_b32 s76, -2
	s_waitcnt lgkmcnt(0)
	v_mov_b32_e32 v1, v0
	v_mov_b32_e32 v2, v0
	v_mov_b32_e32 v3, v0
	v_mov_b32_e32 v4, v0
	v_mov_b32_e32 v5, v0
	v_mov_b32_e32 v6, v0
	v_mov_b32_e32 v7, v0
	v_mov_b32_e32 v16, v0
	v_mov_b32_e32 v17, v0
	v_mov_b32_e32 v18, v0
	v_mov_b32_e32 v19, v0
	v_mov_b32_e32 v20, v0
	v_mov_b32_e32 v21, v0
	v_mov_b32_e32 v22, v0
	v_mov_b32_e32 v23, v0
	v_mov_b32_e32 v32, v0
	v_mov_b32_e32 v33, v0
	v_mov_b32_e32 v34, v0
	v_mov_b32_e32 v35, v0
	v_mov_b32_e32 v36, v0
	v_mov_b32_e32 v37, v0
	v_mov_b32_e32 v38, v0
	v_mov_b32_e32 v39, v0
	v_mov_b32_e32 v48, v0
	v_mov_b32_e32 v49, v0
	v_mov_b32_e32 v50, v0
	v_mov_b32_e32 v51, v0
	v_mov_b32_e32 v52, v0
	v_mov_b32_e32 v53, v0
	v_mov_b32_e32 v54, v0
	v_mov_b32_e32 v55, v0
	v_mov_b32_e32 v8, v0
	v_mov_b32_e32 v9, v0
	v_mov_b32_e32 v10, v0
	v_mov_b32_e32 v11, v0
	v_mov_b32_e32 v12, v0
	v_mov_b32_e32 v13, v0
	v_mov_b32_e32 v14, v0
	v_mov_b32_e32 v15, v0
	v_mov_b32_e32 v24, v0
	v_mov_b32_e32 v25, v0
	v_mov_b32_e32 v26, v0
	v_mov_b32_e32 v27, v0
	v_mov_b32_e32 v28, v0
	v_mov_b32_e32 v29, v0
	v_mov_b32_e32 v30, v0
	v_mov_b32_e32 v31, v0
	v_mov_b32_e32 v40, v0
	v_mov_b32_e32 v41, v0
	v_mov_b32_e32 v42, v0
	v_mov_b32_e32 v43, v0
	v_mov_b32_e32 v44, v0
	v_mov_b32_e32 v45, v0
	v_mov_b32_e32 v46, v0
	v_mov_b32_e32 v47, v0
	v_mov_b32_e32 v56, v0
	v_mov_b32_e32 v57, v0
	v_mov_b32_e32 v58, v0
	v_mov_b32_e32 v59, v0
	v_mov_b32_e32 v60, v0
	v_mov_b32_e32 v61, v0
	v_mov_b32_e32 v62, v0
	v_mov_b32_e32 v63, v0
	v_mov_b32_e32 v64, v0
	v_mov_b32_e32 v65, v0
	v_mov_b32_e32 v66, v0
	v_mov_b32_e32 v67, v0
	v_mov_b32_e32 v68, v0
	v_mov_b32_e32 v69, v0
	v_mov_b32_e32 v70, v0
	v_mov_b32_e32 v71, v0
	v_mov_b32_e32 v80, v0
	v_mov_b32_e32 v81, v0
	v_mov_b32_e32 v82, v0
	v_mov_b32_e32 v83, v0
	v_mov_b32_e32 v84, v0
	v_mov_b32_e32 v85, v0
	v_mov_b32_e32 v86, v0
	v_mov_b32_e32 v87, v0
	v_mov_b32_e32 v96, v0
	v_mov_b32_e32 v97, v0
	v_mov_b32_e32 v98, v0
	v_mov_b32_e32 v99, v0
	v_mov_b32_e32 v100, v0
	v_mov_b32_e32 v101, v0
	v_mov_b32_e32 v102, v0
	v_mov_b32_e32 v103, v0
	v_mov_b32_e32 v112, v0
	v_mov_b32_e32 v113, v0
	v_mov_b32_e32 v114, v0
	v_mov_b32_e32 v115, v0
	v_mov_b32_e32 v116, v0
	v_mov_b32_e32 v117, v0
	v_mov_b32_e32 v118, v0
	v_mov_b32_e32 v119, v0
	v_mov_b32_e32 v72, v0
	v_mov_b32_e32 v73, v0
	v_mov_b32_e32 v74, v0
	v_mov_b32_e32 v75, v0
	v_mov_b32_e32 v76, v0
	v_mov_b32_e32 v77, v0
	v_mov_b32_e32 v78, v0
	v_mov_b32_e32 v79, v0
	v_mov_b32_e32 v88, v0
	v_mov_b32_e32 v89, v0
	v_mov_b32_e32 v90, v0
	v_mov_b32_e32 v91, v0
	v_mov_b32_e32 v92, v0
	v_mov_b32_e32 v93, v0
	v_mov_b32_e32 v94, v0
	v_mov_b32_e32 v95, v0
	v_mov_b32_e32 v104, v0
	v_mov_b32_e32 v105, v0
	v_mov_b32_e32 v106, v0
	v_mov_b32_e32 v107, v0
	v_mov_b32_e32 v108, v0
	v_mov_b32_e32 v109, v0
	v_mov_b32_e32 v110, v0
	v_mov_b32_e32 v111, v0
	v_mov_b32_e32 v120, v0
	v_mov_b32_e32 v121, v0
	v_mov_b32_e32 v122, v0
	v_mov_b32_e32 v123, v0
	v_mov_b32_e32 v124, v0
	v_mov_b32_e32 v125, v0
	v_mov_b32_e32 v126, v0
	v_mov_b32_e32 v127, v0
	.p2alignl 6, 3212836864

.LBB0_638:
	s_ashr_i32 s37, s36, 31
	s_lshl_b64 s[38:39], s[36:37], 20
	s_add_u32 s38, s10, s38
	s_addc_u32 s39, s11, s39
	s_and_b64 s[40:41], s[0:1], exec
	s_cselect_b32 s37, s39, s45
	s_cselect_b32 s67, s38, s44
	s_ashr_i32 s21, s20, 31
	s_lshl_b64 s[40:41], s[20:21], 20
	s_add_u32 s40, s52, s40
	s_addc_u32 s41, s53, s41
	s_and_b64 s[48:49], s[0:1], exec
	s_cselect_b32 s21, s41, s47
	s_cselect_b32 s68, s40, s46
	s_add_u32 s44, s44, 0x80080
	s_addc_u32 s45, s45, 0
	s_add_u32 s69, s46, 0x100
	v_mov_b32_e32 v0, 0
	s_addc_u32 s70, s47, 0
	s_mov_b32 s71, -2
	v_mov_b32_e32 v1, v0
	v_mov_b32_e32 v2, v0
	v_mov_b32_e32 v3, v0
	v_mov_b32_e32 v4, v0
	v_mov_b32_e32 v5, v0
	v_mov_b32_e32 v6, v0
	v_mov_b32_e32 v7, v0
	v_mov_b32_e32 v16, v0
	v_mov_b32_e32 v17, v0
	v_mov_b32_e32 v18, v0
	v_mov_b32_e32 v19, v0
	v_mov_b32_e32 v20, v0
	v_mov_b32_e32 v21, v0
	v_mov_b32_e32 v22, v0
	v_mov_b32_e32 v23, v0
	v_mov_b32_e32 v32, v0
	v_mov_b32_e32 v33, v0
	v_mov_b32_e32 v34, v0
	v_mov_b32_e32 v35, v0
	v_mov_b32_e32 v36, v0
	v_mov_b32_e32 v37, v0
	v_mov_b32_e32 v38, v0
	v_mov_b32_e32 v39, v0
	v_mov_b32_e32 v48, v0
	v_mov_b32_e32 v49, v0
	v_mov_b32_e32 v50, v0
	v_mov_b32_e32 v51, v0
	v_mov_b32_e32 v52, v0
	v_mov_b32_e32 v53, v0
	v_mov_b32_e32 v54, v0
	v_mov_b32_e32 v55, v0
	v_mov_b32_e32 v8, v0
	v_mov_b32_e32 v9, v0
	v_mov_b32_e32 v10, v0
	v_mov_b32_e32 v11, v0
	v_mov_b32_e32 v12, v0
	v_mov_b32_e32 v13, v0
	v_mov_b32_e32 v14, v0
	v_mov_b32_e32 v15, v0
	v_mov_b32_e32 v24, v0
	v_mov_b32_e32 v25, v0
	v_mov_b32_e32 v26, v0
	v_mov_b32_e32 v27, v0
	v_mov_b32_e32 v28, v0
	v_mov_b32_e32 v29, v0
	v_mov_b32_e32 v30, v0
	v_mov_b32_e32 v31, v0
	v_mov_b32_e32 v40, v0
	v_mov_b32_e32 v41, v0
	v_mov_b32_e32 v42, v0
	v_mov_b32_e32 v43, v0
	v_mov_b32_e32 v44, v0
	v_mov_b32_e32 v45, v0
	v_mov_b32_e32 v46, v0
	v_mov_b32_e32 v47, v0
	v_mov_b32_e32 v56, v0
	v_mov_b32_e32 v57, v0
	v_mov_b32_e32 v58, v0
	v_mov_b32_e32 v59, v0
	v_mov_b32_e32 v60, v0
	v_mov_b32_e32 v61, v0
	v_mov_b32_e32 v62, v0
	v_mov_b32_e32 v63, v0
	v_mov_b32_e32 v64, v0
	v_mov_b32_e32 v65, v0
	v_mov_b32_e32 v66, v0
	v_mov_b32_e32 v67, v0
	v_mov_b32_e32 v68, v0
	v_mov_b32_e32 v69, v0
	v_mov_b32_e32 v70, v0
	v_mov_b32_e32 v71, v0
	v_mov_b32_e32 v80, v0
	v_mov_b32_e32 v81, v0
	v_mov_b32_e32 v82, v0
	v_mov_b32_e32 v83, v0
	v_mov_b32_e32 v84, v0
	v_mov_b32_e32 v85, v0
	v_mov_b32_e32 v86, v0
	v_mov_b32_e32 v87, v0
	v_mov_b32_e32 v96, v0
	v_mov_b32_e32 v97, v0
	v_mov_b32_e32 v98, v0
	v_mov_b32_e32 v99, v0
	v_mov_b32_e32 v100, v0
	v_mov_b32_e32 v101, v0
	v_mov_b32_e32 v102, v0
	v_mov_b32_e32 v103, v0
	v_mov_b32_e32 v112, v0
	v_mov_b32_e32 v113, v0
	v_mov_b32_e32 v114, v0
	v_mov_b32_e32 v115, v0
	v_mov_b32_e32 v116, v0
	v_mov_b32_e32 v117, v0
	v_mov_b32_e32 v118, v0
	v_mov_b32_e32 v119, v0
	v_mov_b32_e32 v72, v0
	v_mov_b32_e32 v73, v0
	v_mov_b32_e32 v74, v0
	v_mov_b32_e32 v75, v0
	v_mov_b32_e32 v76, v0
	v_mov_b32_e32 v77, v0
	v_mov_b32_e32 v78, v0
	v_mov_b32_e32 v79, v0
	v_mov_b32_e32 v88, v0
	v_mov_b32_e32 v89, v0
	v_mov_b32_e32 v90, v0
	v_mov_b32_e32 v91, v0
	v_mov_b32_e32 v92, v0
	v_mov_b32_e32 v93, v0
	v_mov_b32_e32 v94, v0
	v_mov_b32_e32 v95, v0
	v_mov_b32_e32 v104, v0
	v_mov_b32_e32 v105, v0
	v_mov_b32_e32 v106, v0
	v_mov_b32_e32 v107, v0
	v_mov_b32_e32 v108, v0
	v_mov_b32_e32 v109, v0
	v_mov_b32_e32 v110, v0
	v_mov_b32_e32 v111, v0
	v_mov_b32_e32 v120, v0
	v_mov_b32_e32 v121, v0
	v_mov_b32_e32 v122, v0
	v_mov_b32_e32 v123, v0
	v_mov_b32_e32 v124, v0
	v_mov_b32_e32 v125, v0
	v_mov_b32_e32 v126, v0
	v_mov_b32_e32 v127, v0
	.p2alignl 6, 3212836864

.LBB0_726:
	s_add_u32 s26, s26, 0x160080
	s_addc_u32 s27, s27, 0
	s_add_u32 s49, s28, 0x100
	v_mov_b32_e32 v0, 0
	s_addc_u32 s50, s29, 0
	s_mov_b32 s51, -2
	v_mov_b32_e32 v1, v0
	v_mov_b32_e32 v2, v0
	v_mov_b32_e32 v3, v0
	v_mov_b32_e32 v4, v0
	v_mov_b32_e32 v5, v0
	v_mov_b32_e32 v6, v0
	v_mov_b32_e32 v7, v0
	v_mov_b32_e32 v16, v0
	v_mov_b32_e32 v17, v0
	v_mov_b32_e32 v18, v0
	v_mov_b32_e32 v19, v0
	v_mov_b32_e32 v20, v0
	v_mov_b32_e32 v21, v0
	v_mov_b32_e32 v22, v0
	v_mov_b32_e32 v23, v0
	v_mov_b32_e32 v32, v0
	v_mov_b32_e32 v33, v0
	v_mov_b32_e32 v34, v0
	v_mov_b32_e32 v35, v0
	v_mov_b32_e32 v36, v0
	v_mov_b32_e32 v37, v0
	v_mov_b32_e32 v38, v0
	v_mov_b32_e32 v39, v0
	v_mov_b32_e32 v48, v0
	v_mov_b32_e32 v49, v0
	v_mov_b32_e32 v50, v0
	v_mov_b32_e32 v51, v0
	v_mov_b32_e32 v52, v0
	v_mov_b32_e32 v53, v0
	v_mov_b32_e32 v54, v0
	v_mov_b32_e32 v55, v0
	v_mov_b32_e32 v8, v0
	v_mov_b32_e32 v9, v0
	v_mov_b32_e32 v10, v0
	v_mov_b32_e32 v11, v0
	v_mov_b32_e32 v12, v0
	v_mov_b32_e32 v13, v0
	v_mov_b32_e32 v14, v0
	v_mov_b32_e32 v15, v0
	v_mov_b32_e32 v24, v0
	v_mov_b32_e32 v25, v0
	v_mov_b32_e32 v26, v0
	v_mov_b32_e32 v27, v0
	v_mov_b32_e32 v28, v0
	v_mov_b32_e32 v29, v0
	v_mov_b32_e32 v30, v0
	v_mov_b32_e32 v31, v0
	v_mov_b32_e32 v40, v0
	v_mov_b32_e32 v41, v0
	v_mov_b32_e32 v42, v0
	v_mov_b32_e32 v43, v0
	v_mov_b32_e32 v44, v0
	v_mov_b32_e32 v45, v0
	v_mov_b32_e32 v46, v0
	v_mov_b32_e32 v47, v0
	v_mov_b32_e32 v56, v0
	v_mov_b32_e32 v57, v0
	v_mov_b32_e32 v58, v0
	v_mov_b32_e32 v59, v0
	v_mov_b32_e32 v60, v0
	v_mov_b32_e32 v61, v0
	v_mov_b32_e32 v62, v0
	v_mov_b32_e32 v63, v0
	v_mov_b32_e32 v64, v0
	v_mov_b32_e32 v65, v0
	v_mov_b32_e32 v66, v0
	v_mov_b32_e32 v67, v0
	v_mov_b32_e32 v68, v0
	v_mov_b32_e32 v69, v0
	v_mov_b32_e32 v70, v0
	v_mov_b32_e32 v71, v0
	v_mov_b32_e32 v80, v0
	v_mov_b32_e32 v81, v0
	v_mov_b32_e32 v82, v0
	v_mov_b32_e32 v83, v0
	v_mov_b32_e32 v84, v0
	v_mov_b32_e32 v85, v0
	v_mov_b32_e32 v86, v0
	v_mov_b32_e32 v87, v0
	v_mov_b32_e32 v96, v0
	v_mov_b32_e32 v97, v0
	v_mov_b32_e32 v98, v0
	v_mov_b32_e32 v99, v0
	v_mov_b32_e32 v100, v0
	v_mov_b32_e32 v101, v0
	v_mov_b32_e32 v102, v0
	v_mov_b32_e32 v103, v0
	v_mov_b32_e32 v112, v0
	v_mov_b32_e32 v113, v0
	v_mov_b32_e32 v114, v0
	v_mov_b32_e32 v115, v0
	v_mov_b32_e32 v116, v0
	v_mov_b32_e32 v117, v0
	v_mov_b32_e32 v118, v0
	v_mov_b32_e32 v119, v0
	v_mov_b32_e32 v72, v0
	v_mov_b32_e32 v73, v0
	v_mov_b32_e32 v74, v0
	v_mov_b32_e32 v75, v0
	v_mov_b32_e32 v76, v0
	v_mov_b32_e32 v77, v0
	v_mov_b32_e32 v78, v0
	v_mov_b32_e32 v79, v0
	v_mov_b32_e32 v88, v0
	v_mov_b32_e32 v89, v0
	v_mov_b32_e32 v90, v0
	v_mov_b32_e32 v91, v0
	v_mov_b32_e32 v92, v0
	v_mov_b32_e32 v93, v0
	v_mov_b32_e32 v94, v0
	v_mov_b32_e32 v95, v0
	v_mov_b32_e32 v104, v0
	v_mov_b32_e32 v105, v0
	v_mov_b32_e32 v106, v0
	v_mov_b32_e32 v107, v0
	v_mov_b32_e32 v108, v0
	v_mov_b32_e32 v109, v0
	v_mov_b32_e32 v110, v0
	v_mov_b32_e32 v111, v0
	v_mov_b32_e32 v120, v0
	v_mov_b32_e32 v121, v0
	v_mov_b32_e32 v122, v0
	v_mov_b32_e32 v123, v0
	v_mov_b32_e32 v124, v0
	v_mov_b32_e32 v125, v0
	v_mov_b32_e32 v126, v0
	v_mov_b32_e32 v127, v0
	.p2alignl 6, 3212836864
